# window loop unmasked path: all 16 V-fragment reads issued up front into free registers, PV MFMAs on counted lgkmcnt waits (was 4 serialized read-wait-MFMA groups)
# speedup vs baseline: 1.0020x; 1.0020x over previous
; DI f32x4 mfma16(bf16x8 a, bf16x8 b, f32x4 c) { return __builtin_amdgcn_mfma_f32_16x16x32_bf16(a, b, c, 0, 0, 0); }
; template <int MODE, bool MASKED, class MaskF>
; DI void flash_tile(const u16* sK, const u16* sV, const bf16x8 (&qf)[2][2], f32x4 (&O)[2][4], float (&m)[2], float (&l)[2],
;                    float (&ps)[4][4], MaskF ok, bool sel, int lane) {
;     ...
;   for (int qt = 0; qt < 2; ++qt) {
;     f32x4 s[4];
;     const float sinit = (MODE == 3) ? ((MASKED || sel) ? m[qt] : -1e30f) : 0.f;
; #pragma unroll
;     for (int kt = 0; kt < 4; ++kt) {
;       s[kt] = f32x4{sinit, sinit, sinit, sinit};
; #pragma unroll
;       for (int ks = 0; ks < 2; ++ks) s[kt] = mfma16(kf[kt][ks], qf[qt][ks], s[kt]);
;     }
;     float pr[4][4];
;     if (MODE == 3) {
;       float rs = 0.f;
; #pragma unroll
;       for (int kt = 0; kt < 4; ++kt)
; #pragma unroll
;         for (int i = 0; i < 4; ++i) {
;           float pv = __builtin_amdgcn_exp2f(s[kt][i]);
;           if (MASKED) pv = ok(kt, i) ? pv : 0.f;
;           pr[kt][i] = pv;
;           rs += pv;
;         }
;       l[qt] += rs;
;     ...
;     if (MODE != 0) {
; #pragma unroll
;       for (int ks2 = 0; ks2 < 2; ++ks2) {
;         pf[qt][ks2].u[0] = pk2(pr[2 * ks2][0], pr[2 * ks2][1]);
;         pf[qt][ks2].u[1] = pk2(pr[2 * ks2][2], pr[2 * ks2][3]);
;         pf[qt][ks2].u[2] = pk2(pr[2 * ks2 + 1][0], pr[2 * ks2 + 1][1]);
;         pf[qt][ks2].u[3] = pk2(pr[2 * ks2 + 1][2], pr[2 * ks2 + 1][3]);
;       }
;     }
;   }
;   if (MODE != 0) {
; #pragma unroll
;     for (int ks2 = 0; ks2 < 2; ++ks2) {
; #pragma unroll
;       for (int dt = 0; dt < 4; ++dt) {
;         union { uint2 h[2]; bf16x8 v; } vf;
;         vf.h[0] = *(const uint2*)(sV + (16 * dt + l15) * 72 + 32 * ks2 + 4 * lg);
;         vf.h[1] = *(const uint2*)(sV + (16 * dt + l15) * 72 + 32 * ks2 + 16 + 4 * lg);
;         O[0][dt] = mfma16(vf.v, pf[0][ks2].v, O[0][dt]);
;         O[1][dt] = mfma16(vf.v, pf[1][ks2].v, O[1][dt]);
;       }
;     }
.LBB0_907:
	v_mov_b32_e32 v29, v28
	v_mov_b32_e32 v30, v28
	v_mov_b32_e32 v31, v28
	v_lshlrev_b32_e32 v159, 1, v2
	s_waitcnt lgkmcnt(7)
	v_mfma_f32_16x16x32_bf16 v[100:103], v[96:99], v[4:7], v[28:31]
	s_waitcnt lgkmcnt(6)
	v_mfma_f32_16x16x32_bf16 v[100:103], v[92:95], v[8:11], v[100:103]
	s_waitcnt lgkmcnt(5)
	v_mfma_f32_16x16x32_bf16 v[104:107], v[88:91], v[4:7], v[28:31]
	s_waitcnt lgkmcnt(4)
	v_mfma_f32_16x16x32_bf16 v[104:107], v[84:87], v[8:11], v[104:107]
	s_nop 3
	v_exp_f32_e32 v25, v100
	v_exp_f32_e32 v27, v101
	v_add_f32_e32 v26, 0, v25
	s_waitcnt lgkmcnt(3)
	v_mfma_f32_16x16x32_bf16 v[108:111], v[80:83], v[4:7], v[28:31]
	v_add_f32_e32 v26, v27, v26
	v_cvt_pk_bf16_f32 v100, v25, v27
	v_mov_b32_e32 v25, v24
	s_waitcnt lgkmcnt(1)
	v_mfma_f32_16x16x32_bf16 v[112:115], v[72:75], v[4:7], v[28:31]
	v_mov_b32_e32 v27, v24
	s_nop 1
	v_exp_f32_e32 v30, v102
	v_exp_f32_e32 v31, v103
	v_mfma_f32_16x16x32_bf16 v[108:111], v[76:79], v[8:11], v[108:111]
	v_exp_f32_e32 v102, v104
	v_exp_f32_e32 v103, v105
	v_add_f32_e32 v26, v30, v26
	v_exp_f32_e32 v104, v106
	v_add_f32_e32 v26, v31, v26
	v_exp_f32_e32 v105, v107
	s_waitcnt lgkmcnt(0)
	v_mfma_f32_16x16x32_bf16 v[112:115], v[68:71], v[8:11], v[112:115]
	v_add_f32_e32 v26, v102, v26
	v_exp_f32_e32 v106, v108
	v_add_f32_e32 v26, v103, v26
	v_exp_f32_e32 v107, v109
	v_add_f32_e32 v26, v104, v26
	v_exp_f32_e32 v108, v110
	v_add_f32_e32 v26, v105, v26
	v_exp_f32_e32 v109, v111
	v_add_f32_e32 v26, v106, v26
	v_exp_f32_e32 v110, v112
	v_add_f32_e32 v26, v107, v26
	v_exp_f32_e32 v111, v113
	v_add_f32_e32 v26, v108, v26
	v_exp_f32_e32 v112, v114
	v_add_f32_e32 v26, v109, v26
	v_exp_f32_e32 v113, v115
	v_add_f32_e32 v26, v110, v26
	v_add_f32_e32 v26, v111, v26
	v_add_f32_e32 v26, v112, v26
	v_add_f32_e32 v26, v113, v26
	v_add_f32_e32 v29, v158, v26
	v_mov_b32_e32 v26, v24
	v_cvt_pk_bf16_f32 v102, v102, v103
	v_cvt_pk_bf16_f32 v103, v104, v105
	v_cvt_pk_bf16_f32 v124, v106, v107
	v_mfma_f32_16x16x32_bf16 v[104:107], v[96:99], v[12:15], v[24:27]
	v_cvt_pk_bf16_f32 v125, v108, v109
	v_cvt_pk_bf16_f32 v126, v110, v111
	v_cvt_pk_bf16_f32 v127, v112, v113
	v_mfma_f32_16x16x32_bf16 v[104:107], v[92:95], v[16:19], v[104:107]
	v_cvt_pk_bf16_f32 v101, v30, v31
	v_mfma_f32_16x16x32_bf16 v[108:111], v[88:91], v[12:15], v[24:27]
	v_mfma_f32_16x16x32_bf16 v[108:111], v[84:87], v[16:19], v[108:111]
	s_nop 4
	v_exp_f32_e32 v30, v106
	v_exp_f32_e32 v31, v107
	v_mfma_f32_16x16x32_bf16 v[112:115], v[80:83], v[12:15], v[24:27]
	v_mfma_f32_16x16x32_bf16 v[116:119], v[72:75], v[12:15], v[24:27]
	v_exp_f32_e32 v106, v108
	v_exp_f32_e32 v107, v109
	v_exp_f32_e32 v108, v110
	v_exp_f32_e32 v25, v104
	v_exp_f32_e32 v27, v105
	v_mfma_f32_16x16x32_bf16 v[112:115], v[76:79], v[16:19], v[112:115]
	v_exp_f32_e32 v109, v111
	v_add_f32_e32 v26, 0, v25
	v_add_f32_e32 v26, v27, v26
	v_add_f32_e32 v26, v30, v26
	v_add_f32_e32 v26, v31, v26
	v_mfma_f32_16x16x32_bf16 v[116:119], v[68:71], v[16:19], v[116:119]
	v_add_f32_e32 v26, v106, v26
	s_nop 0
	v_exp_f32_e32 v110, v112
	v_add_f32_e32 v26, v107, v26
	v_exp_f32_e32 v111, v113
	v_add_f32_e32 v26, v108, v26
	v_exp_f32_e32 v112, v114
	v_add_f32_e32 v26, v109, v26
	v_exp_f32_e32 v113, v115
	v_add_f32_e32 v26, v110, v26
	v_exp_f32_e32 v114, v116
	v_add_f32_e32 v26, v111, v26
	v_exp_f32_e32 v115, v117
	v_add_f32_e32 v26, v112, v26
	v_exp_f32_e32 v116, v118
	v_add_f32_e32 v26, v113, v26
	v_exp_f32_e32 v117, v119
	v_add_f32_e32 v26, v114, v26
	v_cvt_pk_bf16_f32 v104, v25, v27
	v_lshlrev_b32_e32 v25, 1, v0
	v_lshlrev_b32_e32 v27, 1, v153
	v_add_f32_e32 v26, v115, v26
	v_add3_u32 v25, s74, v25, v27
	v_add3_u32 v27, s74, v159, v27
	v_add_f32_e32 v26, v116, v26
	v_cvt_pk_bf16_f32 v105, v30, v31
	v_add_u32_e32 v30, 0x2000, v25
	v_add_u32_e32 v31, 0x2800, v25
	v_add_u32_e32 v25, 0x3000, v25
	v_add_u32_e32 v27, 0x2000, v27
	v_add_f32_e32 v26, v117, v26
	v_cvt_pk_bf16_f32 v106, v106, v107
	v_cvt_pk_bf16_f32 v107, v108, v109
	v_cvt_pk_bf16_f32 v132, v110, v111
	v_cvt_pk_bf16_f32 v135, v116, v117
	ds_read_b64 v[108:109], v30 offset:1024
	ds_read_b64 v[110:111], v30 offset:1056
	ds_read_b64 v[116:117], v31 offset:1280
	ds_read_b64 v[118:119], v31 offset:1312
	ds_read_b64 v[128:129], v25 offset:1536
	ds_read_b64 v[130:131], v25 offset:1568
	ds_read_b64 v[164:165], v27 offset:1024
	ds_read_b64 v[166:167], v27 offset:1056
	ds_read_b64 v[198:199], v30 offset:1088
	ds_read_b64 v[200:201], v30 offset:1120
	ds_read_b64 v[202:203], v31 offset:1344
	ds_read_b64 v[204:205], v31 offset:1376
	ds_read_b64 v[206:207], v25 offset:1600
	ds_read_b64 v[208:209], v25 offset:1632
	ds_read_b64 v[210:211], v27 offset:1088
	ds_read_b64 v[212:213], v27 offset:1120
	v_cvt_pk_bf16_f32 v133, v112, v113
	v_cvt_pk_bf16_f32 v134, v114, v115
	s_waitcnt lgkmcnt(14)
	v_mfma_f32_16x16x32_bf16 v[112:115], v[108:111], v[100:103], v[60:63]
	v_add_f32_e32 v26, v157, v26
	s_waitcnt lgkmcnt(12)
	v_mfma_f32_16x16x32_bf16 v[120:123], v[116:119], v[100:103], v[52:55]
	s_waitcnt lgkmcnt(10)
	v_mfma_f32_16x16x32_bf16 v[160:163], v[128:131], v[100:103], v[44:47]
	s_waitcnt lgkmcnt(8)
	v_mfma_f32_16x16x32_bf16 v[168:171], v[164:167], v[100:103], v[36:39]
	v_mfma_f32_16x16x32_bf16 v[108:111], v[108:111], v[104:107], v[64:67]
	v_mfma_f32_16x16x32_bf16 v[116:119], v[116:119], v[104:107], v[56:59]
	v_mfma_f32_16x16x32_bf16 v[128:131], v[128:131], v[104:107], v[48:51]
	v_mfma_f32_16x16x32_bf16 v[164:167], v[164:167], v[104:107], v[40:43]
	s_waitcnt lgkmcnt(6)
	v_mfma_f32_16x16x32_bf16 v[104:107], v[198:201], v[124:127], v[112:115]
	v_mfma_f32_16x16x32_bf16 v[100:103], v[198:201], v[132:135], v[108:111]
	s_waitcnt lgkmcnt(4)
	v_mfma_f32_16x16x32_bf16 v[112:115], v[202:205], v[124:127], v[120:123]
	v_mfma_f32_16x16x32_bf16 v[108:111], v[202:205], v[132:135], v[116:119]
	s_waitcnt lgkmcnt(2)
	v_mfma_f32_16x16x32_bf16 v[120:123], v[206:209], v[124:127], v[160:163]
	v_mov_b32_e32 v25, v28
	v_mov_b32_e32 v27, v24
	v_mfma_f32_16x16x32_bf16 v[116:119], v[206:209], v[132:135], v[128:131]
	s_waitcnt lgkmcnt(0)
	v_mfma_f32_16x16x32_bf16 v[128:131], v[210:213], v[124:127], v[168:171]
	v_mfma_f32_16x16x32_bf16 v[124:127], v[210:213], v[132:135], v[164:167]
